# NSA: cross-half max exchange in the tile loop and compressed pass 1 via v_permlane32_swap instead of ds_bpermute round trip
# speedup vs baseline: 1.0079x; 1.0079x over previous
; DEV float xor32_f(float v) { return __shfl_xor(v, 32, 64); }
; __device__ void nsa_item(const Params& P, int l, int item, char* smem) {
;     ...
;       for (int kt = 0; kt < ntc; ++kt) {
;         load_kfrag(kn, KCb + (size_t)(((kt + 1 < ntc) ? kt + 1 : kt) * 32 + km) * 64 + hk * 8);
;         const f32x16 s = qk_regs(kf, qf);
; #pragma unroll
;         for (int ks = 0; ks < 4; ++ks) kf[ks] = kn[ks];
;         float sv[16]; float tmax = -1e30f;
; #pragma unroll
;         for (int i = 0; i < 16; ++i) {
;           const int c = kt * 32 + (i & 7) + 8 * hk + 16 * (i >> 3);
;           const int dist = t - (16 * c + 31);
;           sv[i] = (dist >= 0) ? (s[i] * 0.125f - slope * (float)dist) : -1e30f;
;           tmax = fmaxf(tmax, sv[i]);
;         }
;         tmax = fmaxf(tmax, xor32_f(tmax));
;         const float mnew = fmaxf(cm, tmax);
;         float ps = 0.f;
; #pragma unroll
;         for (int i = 0; i < 16; ++i) ps += (sv[i] > -1e29f) ? __expf(sv[i] - mnew) : 0.f;
;         lsum = lsum * __expf(cm - mnew) + ps;
;         cm = mnew;
;       }
.LBB0_157:
	s_add_i32 s1, s2, 1
	s_cmp_lt_u32 s1, s96
	s_cselect_b32 s2, s1, s2
	v_lshl_or_b32 v176, s2, 5, v142
	v_mov_b32_e32 v99, v4
	v_lshlrev_b64 v[4:5], 7, v[176:177]
	v_lshl_add_u64 v[4:5], v[100:101], 0, v[4:5]
	global_load_dwordx4 v[16:19], v[4:5], off
	global_load_dwordx4 v[20:23], v[4:5], off offset:32
	global_load_dwordx4 v[24:27], v[4:5], off offset:64
	global_load_dwordx4 v[28:31], v[4:5], off offset:96
	v_mfma_f32_32x32x16_bf16 v[0:15], v[0:3], v[64:67], 0
	s_mov_b32 s2, 0xf149f2ca
	v_mov_b32_e32 v115, v143
	s_cmp_eq_u32 s96, s1
	v_mfma_f32_32x32x16_bf16 v[0:15], v[36:39], v[68:71], v[0:15]
	v_add_u32_e32 v38, v117, v89
	v_add_u32_e32 v36, 0xfc1, v38
	v_cvt_f32_u32_e32 v179, v36
	v_cmp_lt_i32_e32 vcc, -1, v36
	v_add_u32_e32 v89, 0xfffffe00, v89
	v_mfma_f32_32x32x16_bf16 v[0:15], v[40:43], v[72:75], v[0:15]
	s_waitcnt vmcnt(1)
	v_mov_b64_e32 v[42:43], v[26:27]
	v_mfma_f32_32x32x16_bf16 v[0:15], v[44:47], v[76:79], v[0:15]
	s_waitcnt vmcnt(0)
	v_mov_b64_e32 v[46:47], v[30:31]
	v_mov_b64_e32 v[40:41], v[24:25]
	v_mov_b64_e32 v[44:45], v[28:29]
	s_nop 7
	v_mov_b32_e32 v94, v0
	v_pk_mul_f32 v[36:37], v[94:95], v[178:179]
	v_mov_b32_e32 v94, v1
	v_sub_f32_e32 v0, v36, v37
	v_cndmask_b32_e32 v36, v216, v0, vcc
	v_add_u32_e32 v0, v117, v98
	v_cvt_f32_u32_e32 v179, v0
	v_cmp_lt_i32_e32 vcc, -1, v0
	v_add_u32_e32 v98, 0xfffffe00, v98
	v_pk_mul_f32 v[0:1], v[94:95], v[178:179]
	s_nop 0
	v_sub_f32_e32 v0, v0, v1
	v_cndmask_b32_e32 v37, v216, v0, vcc
	v_add_u32_e32 v0, v117, v91
	v_cvt_f32_u32_e32 v179, v0
	v_mov_b32_e32 v94, v2
	v_cmp_lt_i32_e32 vcc, -1, v0
	v_max3_f32 v39, v36, s2, v37
	v_pk_mul_f32 v[0:1], v[94:95], v[178:179]
	v_mov_b32_e32 v94, v3
	v_sub_f32_e32 v0, v0, v1
	v_cndmask_b32_e32 v2, v216, v0, vcc
	v_add_u32_e32 v0, v117, v90
	v_cvt_f32_u32_e32 v179, v0
	v_cmp_lt_i32_e32 vcc, -1, v0
	v_add_u32_e32 v90, 0xfffffe00, v90
	v_add_u32_e32 v91, 0xfffffe00, v91
	v_pk_mul_f32 v[0:1], v[94:95], v[178:179]
	v_mov_b32_e32 v94, v4
	v_sub_f32_e32 v0, v0, v1
	v_cndmask_b32_e32 v3, v216, v0, vcc
	v_add_u32_e32 v0, 0xf81, v38
	v_cvt_f32_u32_e32 v179, v0
	v_cmp_lt_i32_e32 vcc, -1, v0
	v_max3_f32 v39, v39, v2, v3
	s_mov_b32 s2, s1
	v_pk_mul_f32 v[0:1], v[94:95], v[178:179]
	v_mov_b32_e32 v94, v5
	v_sub_f32_e32 v0, v0, v1
	v_cndmask_b32_e32 v4, v216, v0, vcc
	v_add_u32_e32 v0, v117, v88
	v_cvt_f32_u32_e32 v179, v0
	v_cmp_lt_i32_e32 vcc, -1, v0
	v_add_u32_e32 v88, 0xfffffe00, v88
	v_pk_mul_f32 v[0:1], v[94:95], v[178:179]
	s_nop 0
	v_sub_f32_e32 v0, v0, v1
	v_cndmask_b32_e32 v5, v216, v0, vcc
	v_add_u32_e32 v0, v117, v87
	v_cvt_f32_u32_e32 v179, v0
	v_mov_b32_e32 v94, v6
	v_cmp_lt_i32_e32 vcc, -1, v0
	v_max3_f32 v38, v39, v4, v5
	v_pk_mul_f32 v[0:1], v[94:95], v[178:179]
	v_mov_b32_e32 v94, v7
	v_sub_f32_e32 v0, v0, v1
	v_cndmask_b32_e32 v6, v216, v0, vcc
	v_add_u32_e32 v0, v117, v86
	v_cvt_f32_u32_e32 v179, v0
	v_cmp_lt_i32_e32 vcc, -1, v0
	v_add_u32_e32 v86, 0xfffffe00, v86
	v_add_u32_e32 v87, 0xfffffe00, v87
	v_pk_mul_f32 v[0:1], v[94:95], v[178:179]
	v_mov_b32_e32 v94, v8
	v_sub_f32_e32 v0, v0, v1
	v_cndmask_b32_e32 v7, v216, v0, vcc
	v_add_u32_e32 v0, v117, v85
	v_cvt_f32_u32_e32 v179, v0
	v_cmp_lt_i32_e32 vcc, -1, v0
	v_max3_f32 v38, v38, v6, v7
	v_add_u32_e32 v85, 0xfffffe00, v85
	v_pk_mul_f32 v[0:1], v[94:95], v[178:179]
	v_mov_b32_e32 v94, v9
	v_sub_f32_e32 v0, v0, v1
	v_cndmask_b32_e32 v8, v216, v0, vcc
	v_add_u32_e32 v0, v117, v84
	v_cvt_f32_u32_e32 v179, v0
	v_cmp_lt_i32_e32 vcc, -1, v0
	v_add_u32_e32 v84, 0xfffffe00, v84
	v_pk_mul_f32 v[0:1], v[94:95], v[178:179]
	s_nop 0
	v_sub_f32_e32 v0, v0, v1
	v_cndmask_b32_e32 v9, v216, v0, vcc
	v_add_u32_e32 v0, v117, v83
	v_cvt_f32_u32_e32 v179, v0
	v_mov_b32_e32 v94, v10
	v_cmp_lt_i32_e32 vcc, -1, v0
	v_max3_f32 v38, v38, v8, v9
	v_pk_mul_f32 v[0:1], v[94:95], v[178:179]
	v_mov_b32_e32 v94, v11
	v_sub_f32_e32 v0, v0, v1
	v_cndmask_b32_e32 v10, v216, v0, vcc
	v_add_u32_e32 v0, v117, v82
	v_cvt_f32_u32_e32 v179, v0
	v_cmp_lt_i32_e32 vcc, -1, v0
	v_add_u32_e32 v82, 0xfffffe00, v82
	v_add_u32_e32 v83, 0xfffffe00, v83
	v_pk_mul_f32 v[0:1], v[94:95], v[178:179]
	v_mov_b32_e32 v94, v12
	v_sub_f32_e32 v0, v0, v1
	v_cndmask_b32_e32 v11, v216, v0, vcc
	v_add_u32_e32 v0, v117, v81
	v_cvt_f32_u32_e32 v179, v0
	v_cmp_lt_i32_e32 vcc, -1, v0
	v_max3_f32 v38, v38, v10, v11
	v_add_u32_e32 v81, 0xfffffe00, v81
	v_pk_mul_f32 v[0:1], v[94:95], v[178:179]
	v_mov_b32_e32 v94, v13
	v_sub_f32_e32 v0, v0, v1
	v_cndmask_b32_e32 v12, v216, v0, vcc
	v_add_u32_e32 v0, v117, v80
	v_cvt_f32_u32_e32 v179, v0
	v_cmp_lt_i32_e32 vcc, -1, v0
	v_add_u32_e32 v80, 0xfffffe00, v80
	v_pk_mul_f32 v[0:1], v[94:95], v[178:179]
	s_nop 0
	v_sub_f32_e32 v0, v0, v1
	v_cndmask_b32_e32 v13, v216, v0, vcc
	v_add_u32_e32 v0, v117, v63
	v_cvt_f32_u32_e32 v179, v0
	v_mov_b32_e32 v94, v14
	v_cmp_lt_i32_e32 vcc, -1, v0
	v_max3_f32 v38, v38, v12, v13
	v_pk_mul_f32 v[0:1], v[94:95], v[178:179]
	v_mov_b32_e32 v94, v15
	v_sub_f32_e32 v0, v0, v1
	v_cndmask_b32_e32 v14, v216, v0, vcc
	v_add_u32_e32 v0, v117, v62
	v_cvt_f32_u32_e32 v179, v0
	v_cmp_lt_i32_e32 vcc, -1, v0
	v_add_u32_e32 v62, 0xfffffe00, v62
	v_add_u32_e32 v63, 0xfffffe00, v63
	v_pk_mul_f32 v[0:1], v[94:95], v[178:179]
	s_nop 0
	v_sub_f32_e32 v0, v0, v1
	v_cndmask_b32_e32 v0, v216, v0, vcc
	v_max3_f32 v1, v38, v14, v0
	v_mov_b32_e32 v15, v1
	v_cmp_lt_f32_e32 vcc, s66, v36
	s_nop 0
	v_permlane32_swap_b32_e32 v1, v15
	s_waitcnt lgkmcnt(0)
; DEV float xor32_f(float v) { return __shfl_xor(v, 32, 64); }
; __device__ void nsa_item(const Params& P, int l, int item, char* smem) {
;     ...
;         const float mnew = fmaxf(cm, tmax);
;         float ps = 0.f;
; #pragma unroll
;         for (int i = 0; i < 16; ++i) ps += (sv[i] > -1e29f) ? __expf(sv[i] - mnew) : 0.f;
;         lsum = lsum * __expf(cm - mnew) + ps;
;         cm = mnew;
;       }
;       lsum += xor32_f(lsum);
;       cinv = (lsum > 0.f) ? 1.f / lsum : 0.f;
;     }
;     f32x16 co0, co1;
; #pragma unroll
;     for (int i = 0; i < 16; ++i) { co0[i] = 0.f; co1[i] = 0.f; }
	v_max3_f32 v143, v115, v1, v15
	v_sub_f32_e32 v1, v36, v143
	v_mul_f32_e32 v1, 0x3fb8aa3b, v1
	v_exp_f32_e32 v1, v1
	v_sub_f32_e32 v15, v37, v143
	v_mul_f32_e32 v15, 0x3fb8aa3b, v15
	v_exp_f32_e32 v15, v15
	v_add_f32_e32 v1, 0, v1
	v_cndmask_b32_e32 v1, 0, v1, vcc
	v_cmp_lt_f32_e32 vcc, s66, v37
	v_mov_b64_e32 v[38:39], v[22:23]
	v_mov_b64_e32 v[36:37], v[20:21]
	v_cndmask_b32_e32 v15, 0, v15, vcc
	v_cmp_lt_f32_e32 vcc, s66, v2
	v_sub_f32_e32 v2, v2, v143
	v_mul_f32_e32 v2, 0x3fb8aa3b, v2
	v_exp_f32_e32 v2, v2
	v_add_f32_e32 v1, v15, v1
	v_cndmask_b32_e32 v2, 0, v2, vcc
	v_add_f32_e32 v1, v2, v1
	v_sub_f32_e32 v2, v3, v143
	v_mul_f32_e32 v2, 0x3fb8aa3b, v2
	v_exp_f32_e32 v2, v2
	v_cmp_lt_f32_e32 vcc, s66, v3
	s_nop 1
	v_cndmask_b32_e32 v2, 0, v2, vcc
	v_add_f32_e32 v1, v2, v1
	v_sub_f32_e32 v2, v4, v143
	v_mul_f32_e32 v2, 0x3fb8aa3b, v2
	v_exp_f32_e32 v2, v2
	v_cmp_lt_f32_e32 vcc, s66, v4
	s_nop 1
	v_cndmask_b32_e32 v2, 0, v2, vcc
	v_add_f32_e32 v1, v2, v1
	v_sub_f32_e32 v2, v5, v143
	v_mul_f32_e32 v2, 0x3fb8aa3b, v2
	v_exp_f32_e32 v2, v2
	v_cmp_lt_f32_e32 vcc, s66, v5
	s_nop 1
	v_cndmask_b32_e32 v2, 0, v2, vcc
	v_add_f32_e32 v1, v2, v1
	v_sub_f32_e32 v2, v6, v143
	v_mul_f32_e32 v2, 0x3fb8aa3b, v2
	v_exp_f32_e32 v2, v2
	v_cmp_lt_f32_e32 vcc, s66, v6
	s_nop 1
	v_cndmask_b32_e32 v2, 0, v2, vcc
	v_add_f32_e32 v1, v2, v1
	v_sub_f32_e32 v2, v7, v143
	v_mul_f32_e32 v2, 0x3fb8aa3b, v2
	v_exp_f32_e32 v2, v2
	v_cmp_lt_f32_e32 vcc, s66, v7
	s_nop 1
	v_cndmask_b32_e32 v2, 0, v2, vcc
	v_add_f32_e32 v1, v2, v1
	v_sub_f32_e32 v2, v8, v143
	v_mul_f32_e32 v2, 0x3fb8aa3b, v2
	v_exp_f32_e32 v2, v2
	v_cmp_lt_f32_e32 vcc, s66, v8
	s_nop 1
	v_cndmask_b32_e32 v2, 0, v2, vcc
	v_add_f32_e32 v1, v2, v1
	v_sub_f32_e32 v2, v9, v143
	v_mul_f32_e32 v2, 0x3fb8aa3b, v2
	v_exp_f32_e32 v2, v2
	v_cmp_lt_f32_e32 vcc, s66, v9
	s_nop 1
	v_cndmask_b32_e32 v2, 0, v2, vcc
	v_add_f32_e32 v1, v2, v1
	v_sub_f32_e32 v2, v10, v143
	v_mul_f32_e32 v2, 0x3fb8aa3b, v2
	v_exp_f32_e32 v2, v2
	v_cmp_lt_f32_e32 vcc, s66, v10
	s_nop 1
	v_cndmask_b32_e32 v2, 0, v2, vcc
	v_add_f32_e32 v1, v2, v1
	v_sub_f32_e32 v2, v11, v143
	v_mul_f32_e32 v2, 0x3fb8aa3b, v2
	v_exp_f32_e32 v2, v2
	v_cmp_lt_f32_e32 vcc, s66, v11
	s_nop 1
	v_cndmask_b32_e32 v2, 0, v2, vcc
	v_add_f32_e32 v1, v2, v1
	v_sub_f32_e32 v2, v12, v143
	v_mul_f32_e32 v2, 0x3fb8aa3b, v2
	v_exp_f32_e32 v2, v2
	v_cmp_lt_f32_e32 vcc, s66, v12
	s_nop 1
	v_cndmask_b32_e32 v2, 0, v2, vcc
	v_add_f32_e32 v1, v2, v1
	v_sub_f32_e32 v2, v13, v143
	v_mul_f32_e32 v2, 0x3fb8aa3b, v2
	v_exp_f32_e32 v2, v2
	v_cmp_lt_f32_e32 vcc, s66, v13
	s_nop 1
	v_cndmask_b32_e32 v2, 0, v2, vcc
	v_add_f32_e32 v1, v2, v1
	v_sub_f32_e32 v2, v14, v143
	v_mul_f32_e32 v2, 0x3fb8aa3b, v2
	v_exp_f32_e32 v2, v2
	v_cmp_lt_f32_e32 vcc, s66, v14
	s_nop 1
	v_cndmask_b32_e32 v2, 0, v2, vcc
	v_cmp_lt_f32_e32 vcc, s66, v0
	v_sub_f32_e32 v0, v0, v143
	v_mul_f32_e32 v0, 0x3fb8aa3b, v0
	v_exp_f32_e32 v0, v0
	v_add_f32_e32 v1, v2, v1
	v_cndmask_b32_e32 v0, 0, v0, vcc
	v_add_f32_e32 v4, v0, v1
	v_sub_f32_e32 v0, v115, v143
	v_mul_f32_e32 v0, 0x3fb8aa3b, v0
	v_exp_f32_e32 v0, v0
	s_nop 0
	v_fmac_f32_e32 v4, v99, v0
	v_mov_b64_e32 v[0:1], v[16:17]
	v_mov_b64_e32 v[2:3], v[18:19]
	s_cbranch_scc0 .LBB0_157
	ds_bpermute_b32 v0, v139, v4
	s_lshl_b32 s62, s0, 6
	s_mov_b32 s63, s3
	v_lshlrev_b32_e32 v176, 9, v117
	v_subrev_u32_e32 v116, 31, v61
	s_waitcnt lgkmcnt(0)
	v_add_f32_e32 v0, v4, v0
	v_div_scale_f32 v1, s[0:1], v0, v0, 1.0
	v_rcp_f32_e32 v2, v1
	s_lshl_b64 s[0:1], s[62:63], 9
	s_add_u32 s0, s80, s0
	s_addc_u32 s1, s81, s1
	v_fma_f32 v3, -v1, v2, 1.0
	v_fmac_f32_e32 v2, v3, v2
	v_div_scale_f32 v3, vcc, 1.0, v0, 1.0
	v_mul_f32_e32 v4, v3, v2
	v_fma_f32 v5, -v1, v4, v3
	v_fmac_f32_e32 v4, v5, v2
	v_fma_f32 v1, -v1, v4, v3
	v_div_fmas_f32 v1, v1, v2, v4
	v_div_fixup_f32 v1, v1, v0, 1.0
	v_cmp_lt_f32_e32 vcc, 0, v0
	v_lshlrev_b32_e32 v0, 13, v60
	v_mov_b32_e32 v145, 0
	v_cndmask_b32_e32 v118, 0, v1, vcc
	v_lshlrev_b32_e32 v1, 8, v117
	s_mov_b32 s42, 0
	v_or3_b32 v144, v0, v1, v92
	v_lshl_add_u64 v[0:1], s[0:1], 0, v[176:177]
	v_lshlrev_b32_e32 v98, 1, v92
	v_mov_b32_e32 v99, v177
	v_or_b32_e32 v115, 4, v92
	v_cmp_eq_u32_e64 s[40:41], 0, v141
	v_lshl_add_u64 v[120:121], v[0:1], 0, v[98:99]
	v_mov_b32_e32 v99, v116
	v_mov_b32_e32 v119, v118
	s_mov_b32 s2, s42
	s_mov_b32 s0, 0
	v_mov_b32_e32 v0, 0
	v_mov_b32_e32 v1, v145
	v_mov_b32_e32 v2, v145
	v_mov_b32_e32 v3, v145
	v_mov_b32_e32 v4, v145
	v_mov_b32_e32 v5, v145
	v_mov_b32_e32 v6, v145
	v_mov_b32_e32 v7, v145
	v_mov_b32_e32 v8, v145
	v_mov_b32_e32 v9, v145
	v_mov_b32_e32 v10, v145
	v_mov_b32_e32 v11, v145
	v_mov_b32_e32 v12, v145
	v_mov_b32_e32 v13, v145
	v_mov_b32_e32 v14, v145
	v_mov_b32_e32 v15, v145
	v_mov_b32_e32 v16, 0
	v_mov_b32_e32 v17, v145
	v_mov_b32_e32 v18, v145
	v_mov_b32_e32 v19, v145
	v_mov_b32_e32 v20, v145
	v_mov_b32_e32 v21, v145
	v_mov_b32_e32 v22, v145
	v_mov_b32_e32 v23, v145
	v_mov_b32_e32 v24, v145
	v_mov_b32_e32 v25, v145
	v_mov_b32_e32 v26, v145
	v_mov_b32_e32 v27, v145
	v_mov_b32_e32 v28, v145
	v_mov_b32_e32 v29, v145
	v_mov_b32_e32 v30, v145
	v_mov_b32_e32 v31, v145

; DEV float xor32_f(float v) { return __shfl_xor(v, 32, 64); }
; DEV void att_tile64(AttAcc& A, const f32x16& s0, const f32x16& s1, float qs, float slope2, int dt, float lane_bias, bool masked, int wlim,
;                     const bf16_t* vt, size_t vstride) {
;     ...
;   float tmax = sc[0];
; #pragma unroll
;   for (int i = 1; i < 32; ++i) tmax = fmaxf(tmax, sc[i]);
;   tmax = fmaxf(tmax, xor32_f(tmax));
;   if (__any(tmax > A.m)) {
;     const float mnew = fmaxf(A.m, tmax);
;     const float alpha = __builtin_amdgcn_exp2f(A.m - mnew);
;     A.m = mnew;
;     A.l *= alpha;
; #pragma unroll
;     for (int i = 0; i < 16; ++i) { A.o0[i] *= alpha; A.o1[i] *= alpha; }
;   }
.LBB0_186:
	v_max_f32_e32 v46, v119, v119
	v_max_f32_e32 v47, v118, v118
	v_max_f32_e32 v46, v47, v46
	v_max3_f32 v46, v46, v120, v121
	v_max3_f32 v46, v46, v52, v53
	v_max3_f32 v46, v46, v54, v55
	v_max3_f32 v46, v46, v56, v57
	v_max3_f32 v46, v46, v58, v59
	v_max3_f32 v46, v46, v42, v43
	v_max3_f32 v46, v46, v44, v45
	v_max3_f32 v46, v46, v116, v117
	v_max3_f32 v46, v46, v50, v51
	v_max3_f32 v46, v46, v48, v49
	v_max3_f32 v46, v46, v34, v35
	v_max3_f32 v46, v46, v36, v37
	v_max3_f32 v46, v46, v38, v39
	v_max3_f32 v46, v46, v40, v41
	v_max3_f32 v46, v46, v32, v33
	v_mov_b32_e32 v47, v46
	s_nop 1
	v_permlane32_swap_b32_e32 v46, v47
	v_max_f32_e32 v47, v47, v47
	v_max_f32_e32 v46, v46, v47
	v_cmp_gt_f32_e32 vcc, v46, v158
	s_cbranch_vccz .LBB0_188
	v_max_f32_e32 v46, v46, v46
	v_max_f32_e32 v47, v158, v158
	v_max_f32_e32 v47, v47, v46
	v_sub_f32_e32 v46, v158, v47
	v_exp_f32_e32 v46, v46
	v_mov_b32_e32 v158, v47
	v_mul_f32_e32 v156, v156, v46
	v_pk_mul_f32 v[14:15], v[14:15], v[46:47] op_sel_hi:[1,0]
	v_pk_mul_f32 v[12:13], v[12:13], v[46:47] op_sel_hi:[1,0]
	v_pk_mul_f32 v[10:11], v[10:11], v[46:47] op_sel_hi:[1,0]
	v_pk_mul_f32 v[8:9], v[8:9], v[46:47] op_sel_hi:[1,0]
	v_pk_mul_f32 v[6:7], v[6:7], v[46:47] op_sel_hi:[1,0]
	v_pk_mul_f32 v[4:5], v[4:5], v[46:47] op_sel_hi:[1,0]
	v_pk_mul_f32 v[2:3], v[2:3], v[46:47] op_sel_hi:[1,0]
	v_pk_mul_f32 v[0:1], v[0:1], v[46:47] op_sel_hi:[1,0]
	v_pk_mul_f32 v[30:31], v[30:31], v[46:47] op_sel_hi:[1,0]
	v_pk_mul_f32 v[28:29], v[28:29], v[46:47] op_sel_hi:[1,0]
	v_pk_mul_f32 v[26:27], v[26:27], v[46:47] op_sel_hi:[1,0]
	v_pk_mul_f32 v[24:25], v[24:25], v[46:47] op_sel_hi:[1,0]
	v_pk_mul_f32 v[22:23], v[22:23], v[46:47] op_sel_hi:[1,0]
	v_pk_mul_f32 v[20:21], v[20:21], v[46:47] op_sel_hi:[1,0]
	v_pk_mul_f32 v[18:19], v[18:19], v[46:47] op_sel_hi:[1,0]
	v_pk_mul_f32 v[16:17], v[16:17], v[46:47] op_sel_hi:[1,0]
